# layer-1 input rmsnorm and final rmsnorm: rows assigned so each workgroup normalises rows of M-tiles produced/consumed on its own XCD (b%8), when gridDim==256
# speedup vs baseline: 1.0089x; 1.0089x over previous
; DI int otid() { int t = threadIdx.x; asm volatile("" : "+v"(t)); return t; }
; DI void rmsnorm_phase(const float* __restrict__ X, const float* __restrict__ g, bf16_t* __restrict__ H, float* __restrict__ OF) {
;   const int tid = otid(), lane = tid & 63;
;   const int gw = blockIdx.x * NWV + (tid >> 6), nw = gridDim.x * NWV;
;   for (int row = gw; row < T; row += nw) {
;     const float* xr = X + (size_t)row * D;
;     f32x4 v[8];
;     float ss = 0.f;
; #pragma unroll
;     for (int i = 0; i < 8; ++i) { v[i] = *(const f32x4*)(xr + lane * 4 + 256 * i); ss += v[i][0] * v[i][0] + v[i][1] * v[i][1] + v[i][2] * v[i][2] + v[i][3] * v[i][3]; }
;     ss = wave_sum(ss);
;     const float rstd = rsqrtf(ss * (1.f / D) + EPS);
; #pragma unroll
;     for (int i = 0; i < 8; ++i) {
;       const f32x4 gg = *(const f32x4*)(g + lane * 4 + 256 * i);
;       f32x4 o = v[i] * rstd * gg;
;       if (H) { u32x2 w; w.x = pk_bf16(o[0], o[1]); w.y = pk_bf16(o[2], o[3]); *(u32x2*)(H + (size_t)row * D + lane * 4 + 256 * i) = w; }
;       else *(f32x4*)(OF + (size_t)row * D + lane * 4 + 256 * i) = o;
;     }
;   }
; }
.LBB0_819:
	s_or_b64 exec, exec, s[0:1]
	v_mov_b32_e32 v32, v206
	s_waitcnt lgkmcnt(0)
	s_barrier
	v_readlane_b32 s0, v252, 38
	v_ashrrev_i32_e32 v0, 6, v32
	s_lshl_b32 s26, s96, 3
	v_add_u32_e32 v48, s0, v0
	s_cmp_lg_u32 s96, 0x100
	s_cbranch_scc1 .Lxr_0
	s_lshr_b32 s99, s0, 3
	s_and_b32 s98, s99, 7
	s_lshl_b32 s98, s98, 8
	s_and_b32 s99, s99, 0xf8
	s_add_i32 s98, s98, s99
	v_add_u32_e32 v48, s98, v0
.Lxr_0:
	s_movk_i32 s0, 0x4000
	v_cmp_gt_i32_e32 vcc, s0, v48
	s_and_saveexec_b64 s[0:1], vcc
	s_cbranch_execz .LBB0_822
	v_lshlrev_b32_e32 v0, 4, v32
	v_and_b32_e32 v0, 0x3f0, v0
	v_mov_b32_e32 v1, 0
	v_lshl_add_u64 v[0:1], s[70:71], 0, v[0:1]
	s_mov_b64 s[2:3], 0x2000
	v_lshl_add_u64 v[34:35], v[0:1], 0, s[2:3]
	s_movk_i32 s2, 0x3000
	v_add_co_u32_e32 v36, vcc, s2, v0
	v_mbcnt_hi_u32_b32 v33, -1, v207
	s_nop 0
	v_addc_co_u32_e32 v37, vcc, 0, v1, vcc
	global_load_dwordx4 v[0:3], v[34:35], off offset:1024
	global_load_dwordx4 v[4:7], v[34:35], off offset:2048
	global_load_dwordx4 v[8:11], v[36:37], off offset:-4096
	global_load_dwordx4 v[12:15], v[34:35], off offset:3072
	global_load_dwordx4 v[16:19], v[36:37], off
	global_load_dwordx4 v[20:23], v[36:37], off offset:1024
	global_load_dwordx4 v[24:27], v[36:37], off offset:2048
	global_load_dwordx4 v[28:31], v[36:37], off offset:3072
	v_and_b32_e32 v34, 64, v33
	v_add_u32_e32 v34, 64, v34
	v_xor_b32_e32 v35, 32, v33
	v_cmp_lt_i32_e32 vcc, v35, v34
	v_ashrrev_i32_e32 v49, 31, v48
	v_and_b32_e32 v36, 63, v32
	v_cndmask_b32_e32 v35, v33, v35, vcc
	v_lshlrev_b32_e32 v54, 2, v35
	v_xor_b32_e32 v35, 16, v33
	v_cmp_lt_i32_e32 vcc, v35, v34
	s_mov_b64 s[2:3], 0x1000
	s_ashr_i32 s27, s26, 31
	v_cndmask_b32_e32 v35, v33, v35, vcc
	v_lshlrev_b32_e32 v55, 2, v35
	v_xor_b32_e32 v35, 8, v33
	v_cmp_lt_i32_e32 vcc, v35, v34
	s_mov_b64 s[6:7], 0x40c0000
	s_mov_b64 s[8:9], 0
	v_cndmask_b32_e32 v35, v33, v35, vcc
	v_lshlrev_b32_e32 v56, 2, v35
	v_xor_b32_e32 v35, 4, v33
	v_cmp_lt_i32_e32 vcc, v35, v34
	s_mov_b32 s10, 0x800000
	s_movk_i32 s11, 0x3fff
	v_cndmask_b32_e32 v35, v33, v35, vcc
	v_lshlrev_b32_e32 v57, 2, v35
	v_xor_b32_e32 v35, 2, v33
	v_cmp_lt_i32_e32 vcc, v35, v34
	s_nop 1
	v_cndmask_b32_e32 v35, v33, v35, vcc
	v_lshlrev_b32_e32 v58, 2, v35
	v_xor_b32_e32 v35, 1, v33
	v_cmp_lt_i32_e32 vcc, v35, v34
	s_nop 1
	v_cndmask_b32_e32 v33, v33, v35, vcc
	v_lshlrev_b64 v[34:35], 13, v[48:49]
	v_lshl_or_b32 v34, v36, 4, v34
	v_lshlrev_b32_e32 v59, 2, v33
	v_lshl_add_u64 v[32:33], s[20:21], 0, v[34:35]
	v_lshl_add_u64 v[50:51], v[32:33], 0, s[2:3]
	v_lshlrev_b64 v[32:33], 12, v[48:49]
	v_lshl_or_b32 v32, v36, 3, v32
	v_lshl_add_u64 v[32:33], s[22:23], 0, v[32:33]
	s_lshl_b64 s[2:3], s[26:27], 13
	v_lshl_add_u64 v[52:53], v[32:33], 0, s[6:7]
	s_lshl_b64 s[6:7], s[26:27], 12
	v_mov_b32_e32 v49, 0x358637bd

; DI int otid() { int t = threadIdx.x; asm volatile("" : "+v"(t)); return t; }
; DI void rmsnorm_phase(const float* __restrict__ X, const float* __restrict__ g, bf16_t* __restrict__ H, float* __restrict__ OF) {
;   const int tid = otid(), lane = tid & 63;
;   const int gw = blockIdx.x * NWV + (tid >> 6), nw = gridDim.x * NWV;
;   for (int row = gw; row < T; row += nw) {
;     const float* xr = X + (size_t)row * D;
;     f32x4 v[8];
;     float ss = 0.f;
; #pragma unroll
;     for (int i = 0; i < 8; ++i) { v[i] = *(const f32x4*)(xr + lane * 4 + 256 * i); ss += v[i][0] * v[i][0] + v[i][1] * v[i][1] + v[i][2] * v[i][2] + v[i][3] * v[i][3]; }
;     ss = wave_sum(ss);
;     const float rstd = rsqrtf(ss * (1.f / D) + EPS);
; #pragma unroll
;     for (int i = 0; i < 8; ++i) {
;       const f32x4 gg = *(const f32x4*)(g + lane * 4 + 256 * i);
;       f32x4 o = v[i] * rstd * gg;
;       if (H) { u32x2 w; w.x = pk_bf16(o[0], o[1]); w.y = pk_bf16(o[2], o[3]); *(u32x2*)(H + (size_t)row * D + lane * 4 + 256 * i) = w; }
;       else *(f32x4*)(OF + (size_t)row * D + lane * 4 + 256 * i) = o;
;     }
;   }
; }
.LBB0_1707:
	s_or_b64 exec, exec, s[0:1]
	s_waitcnt lgkmcnt(0)
	s_barrier
	v_readlane_b32 s0, v252, 38
	v_ashrrev_i32_e32 v0, 6, v206
	s_nop 0
	v_add_u32_e32 v32, s0, v0
	s_cmp_lg_u32 s96, 0x100
	s_cbranch_scc1 .Lxr_1
	s_lshr_b32 s99, s0, 3
	s_and_b32 s98, s99, 7
	s_lshl_b32 s98, s98, 8
	s_and_b32 s99, s99, 0xf8
	s_add_i32 s98, s98, s99
	v_add_u32_e32 v32, s98, v0
.Lxr_1:
	s_movk_i32 s0, 0x4000
	v_cmp_gt_i32_e32 vcc, s0, v32
	s_and_saveexec_b64 s[0:1], vcc
	s_cbranch_execz .LBB0_1710
	v_lshlrev_b32_e32 v0, 4, v206
	v_and_b32_e32 v16, 0x3f0, v0
	v_mov_b32_e32 v17, 0
	v_lshl_add_u64 v[18:19], s[72:73], 0, v[16:17]
	s_movk_i32 s0, 0x1000
	v_add_co_u32_e32 v34, vcc, s0, v18
	global_load_dwordx4 v[0:3], v16, s[72:73]
	global_load_dwordx4 v[4:7], v16, s[72:73] offset:1024
	global_load_dwordx4 v[8:11], v16, s[72:73] offset:2048
	global_load_dwordx4 v[12:15], v16, s[72:73] offset:3072
	v_addc_co_u32_e32 v35, vcc, 0, v19, vcc
	global_load_dwordx4 v[16:19], v[34:35], off
	global_load_dwordx4 v[20:23], v[34:35], off offset:1024
	global_load_dwordx4 v[24:27], v[34:35], off offset:2048
	global_load_dwordx4 v[28:31], v[34:35], off offset:3072
	v_and_b32_e32 v33, 64, v198
	v_add_u32_e32 v33, 64, v33
	v_xor_b32_e32 v34, 32, v198
	v_cmp_lt_i32_e32 vcc, v34, v33
	s_mov_b64 s[0:1], 0x1000
	s_ashr_i32 s27, s26, 31
	v_cndmask_b32_e32 v34, v198, v34, vcc
	v_lshlrev_b32_e32 v36, 2, v34
	v_xor_b32_e32 v34, 16, v198
	v_cmp_lt_i32_e32 vcc, v34, v33
	s_lshl_b64 s[2:3], s[26:27], 13
	s_mov_b64 s[4:5], 0
	v_cndmask_b32_e32 v34, v198, v34, vcc
	v_lshlrev_b32_e32 v37, 2, v34
	v_xor_b32_e32 v34, 8, v198
	v_cmp_lt_i32_e32 vcc, v34, v33
	s_mov_b32 s6, 0x800000
	s_movk_i32 s7, 0x3fff
	v_cndmask_b32_e32 v34, v198, v34, vcc
	v_lshlrev_b32_e32 v38, 2, v34
	v_xor_b32_e32 v34, 4, v198
	v_cmp_lt_i32_e32 vcc, v34, v33
	s_nop 1
	v_cndmask_b32_e32 v34, v198, v34, vcc
	v_lshlrev_b32_e32 v39, 2, v34
	v_xor_b32_e32 v34, 2, v198
	v_cmp_lt_i32_e32 vcc, v34, v33
	s_nop 1
	v_cndmask_b32_e32 v34, v198, v34, vcc
	v_lshlrev_b32_e32 v40, 2, v34
	v_xor_b32_e32 v34, 1, v198
	v_cmp_lt_i32_e32 vcc, v34, v33
	s_nop 1
	v_cndmask_b32_e32 v33, v198, v34, vcc
	v_lshlrev_b32_e32 v41, 2, v33
	v_ashrrev_i32_e32 v33, 31, v32
	v_lshlrev_b64 v[34:35], 13, v[32:33]
	v_and_b32_e32 v33, 63, v206
	v_lshl_or_b32 v34, v33, 4, v34
	v_lshl_add_u64 v[34:35], s[20:21], 0, v[34:35]
	v_lshl_add_u64 v[34:35], v[34:35], 0, s[0:1]
	v_mov_b32_e32 v33, 0x358637bd
